# GLA step 4: o-block MFMA operands swapped (transposed result), one 8-byte store per 16-row block instead of four 2-byte stores, fragment reads issued ahead
# speedup vs baseline: 1.0100x; 1.0028x over previous
.LBB0_3097:
	s_andn2_b64 vcc, exec, s[48:49]
	s_cbranch_vccnz .LBB0_3088
	v_and_b32_e32 v117, 15, v180
	v_bfe_u32 v162, v180, 4, 2
	v_mul_i32_i24_e32 v115, s91, v117
	v_lshlrev_b32_e32 v162, 3, v162
	v_lshlrev_b32_e32 v117, 1, v117
	v_sub_u32_e32 v162, v162, v117
	v_add_u32_e32 v162, 32, v162
	v_mov_b32_e32 v163, 0
	v_lshl_add_u64 v[178:179], v[144:145], 0, v[162:163]
	ds_read2_b64 v[216:219], v205 offset1:4
	ds_read2_b64 v[220:223], v205 offset0:8 offset1:12
	ds_read2_b64 v[224:227], v205 offset0:16 offset1:20
	ds_read2_b64 v[228:231], v205 offset0:24 offset1:28
	ds_read_b128 v[232:235], v208 offset:62464
	ds_read_b128 v[236:239], v208 offset:62528
	v_add_u32_e32 v117, 0x1000, v205
	ds_read2_b64 v[162:165], v117 offset0:32 offset1:36
	ds_read2_b64 v[166:169], v117 offset0:40 offset1:44
	ds_read2_b64 v[170:173], v117 offset0:48 offset1:52
	ds_read2_b64 v[174:177], v117 offset0:56 offset1:60
	v_cvt_pk_bf16_f32 v96, v44, v45
	v_cvt_pk_bf16_f32 v97, v46, v47
	v_cvt_pk_bf16_f32 v98, v52, v53
	v_cvt_pk_bf16_f32 v99, v54, v55
	v_cvt_pk_bf16_f32 v92, v48, v49
	v_cvt_pk_bf16_f32 v93, v50, v51
	v_cvt_pk_bf16_f32 v94, v56, v57
	v_cvt_pk_bf16_f32 v95, v58, v59
	v_cvt_pk_bf16_f32 v88, v60, v61
	v_cvt_pk_bf16_f32 v89, v62, v63
	v_cvt_pk_bf16_f32 v90, v64, v65
	v_cvt_pk_bf16_f32 v91, v66, v67
	v_cvt_pk_bf16_f32 v84, v68, v69
	v_cvt_pk_bf16_f32 v85, v70, v71
	v_cvt_pk_bf16_f32 v86, v72, v73
	v_cvt_pk_bf16_f32 v87, v74, v75
	s_sub_i32 s94, s92, 64
	s_cmp_lt_u32 s93, 4
	s_cselect_b32 s48, 0xff, s85
	s_add_i32 s48, s48, s75
	s_add_i32 s95, s48, 64
	s_and_b64 s[48:49], s[72:73], exec
	s_cselect_b32 s48, s94, s95
	s_lshl_b32 s95, s91, 4
	s_waitcnt lgkmcnt(4)
	v_mfma_f32_16x16x32_bf16 v[216:219], v[96:99], v[216:219], 0
	v_mfma_f32_16x16x32_bf16 v[216:219], v[92:95], v[220:223], v[216:219]
	v_mfma_f32_16x16x32_bf16 v[216:219], v[88:91], v[224:227], v[216:219]
	v_mfma_f32_16x16x32_bf16 v[216:219], v[84:87], v[228:231], v[216:219]
	v_mfma_f32_16x16x32_bf16 v[216:219], v[80:83], v[232:235], v[216:219]
	v_mfma_f32_16x16x32_bf16 v[216:219], v[76:79], v[236:239], v[216:219]
	v_add_u32_e32 v117, 0x2000, v205
	ds_read2_b64 v[224:227], v117 offset0:80 offset1:84
	ds_read2_b64 v[228:231], v117 offset0:88 offset1:92
	ds_read_b128 v[232:235], v208 offset:64768
	ds_read_b128 v[236:239], v208 offset:64832
	v_add_u32_e32 v220, s48, v115
	v_ashrrev_i32_e32 v221, 31, v220
	v_lshl_add_u64 v[220:221], v[220:221], 0, s[70:71]
	v_lshlrev_b64 v[220:221], 11, v[220:221]
	v_lshl_add_u64 v[220:221], v[178:179], 0, v[220:221]
	s_nop 3
	v_cvt_pk_bf16_f32 v222, v216, v217
	v_cvt_pk_bf16_f32 v223, v218, v219
	global_store_dwordx2 v[220:221], v[222:223], off offset:-32
	s_add_i32 s48, s48, s95
	ds_read2_b64 v[216:219], v117 offset0:64 offset1:68
	ds_read2_b64 v[220:223], v117 offset0:72 offset1:76
	s_waitcnt lgkmcnt(2)
	v_mfma_f32_16x16x32_bf16 v[162:165], v[96:99], v[162:165], 0
	v_mfma_f32_16x16x32_bf16 v[162:165], v[92:95], v[166:169], v[162:165]
	v_mfma_f32_16x16x32_bf16 v[162:165], v[88:91], v[170:173], v[162:165]
	v_mfma_f32_16x16x32_bf16 v[162:165], v[84:87], v[174:177], v[162:165]
	v_mfma_f32_16x16x32_bf16 v[162:165], v[80:83], v[232:235], v[162:165]
	v_mfma_f32_16x16x32_bf16 v[162:165], v[76:79], v[236:239], v[162:165]
	v_add_u32_e32 v117, 0x3000, v205
	ds_read2_b64 v[170:173], v117 offset0:112 offset1:116
	ds_read2_b64 v[174:177], v117 offset0:120 offset1:124
	ds_read_b128 v[232:235], v209 offset:62464
	ds_read_b128 v[236:239], v209 offset:62528
	v_add_u32_e32 v166, s48, v115
	v_ashrrev_i32_e32 v167, 31, v166
	v_lshl_add_u64 v[166:167], v[166:167], 0, s[70:71]
	v_lshlrev_b64 v[166:167], 11, v[166:167]
	v_lshl_add_u64 v[166:167], v[178:179], 0, v[166:167]
	s_nop 3
	v_cvt_pk_bf16_f32 v168, v162, v163
	v_cvt_pk_bf16_f32 v169, v164, v165
	global_store_dwordx2 v[166:167], v[168:169], off offset:-32
	s_add_i32 s48, s48, s95
	ds_read2_b64 v[162:165], v117 offset0:96 offset1:100
	ds_read2_b64 v[166:169], v117 offset0:104 offset1:108
	s_waitcnt lgkmcnt(2)
	v_mfma_f32_16x16x32_bf16 v[216:219], v[96:99], v[216:219], 0
	v_mfma_f32_16x16x32_bf16 v[216:219], v[92:95], v[220:223], v[216:219]
	v_mfma_f32_16x16x32_bf16 v[216:219], v[88:91], v[224:227], v[216:219]
	v_mfma_f32_16x16x32_bf16 v[216:219], v[84:87], v[228:231], v[216:219]
	v_mfma_f32_16x16x32_bf16 v[216:219], v[80:83], v[232:235], v[216:219]
	v_mfma_f32_16x16x32_bf16 v[216:219], v[76:79], v[236:239], v[216:219]
	ds_read_b128 v[232:235], v209 offset:64768
	ds_read_b128 v[236:239], v209 offset:64832
	v_add_u32_e32 v220, s48, v115
	v_ashrrev_i32_e32 v221, 31, v220
	v_lshl_add_u64 v[220:221], v[220:221], 0, s[70:71]
	v_lshlrev_b64 v[220:221], 11, v[220:221]
	v_lshl_add_u64 v[220:221], v[178:179], 0, v[220:221]
	s_nop 6
	v_cvt_pk_bf16_f32 v222, v216, v217
	v_cvt_pk_bf16_f32 v223, v218, v219
	global_store_dwordx2 v[220:221], v[222:223], off offset:-32
	s_add_i32 s48, s48, s95
	s_waitcnt lgkmcnt(0)
	v_mfma_f32_16x16x32_bf16 v[162:165], v[96:99], v[162:165], 0
	v_mfma_f32_16x16x32_bf16 v[162:165], v[92:95], v[166:169], v[162:165]
	v_mfma_f32_16x16x32_bf16 v[162:165], v[88:91], v[170:173], v[162:165]
	v_mfma_f32_16x16x32_bf16 v[162:165], v[84:87], v[174:177], v[162:165]
	v_mfma_f32_16x16x32_bf16 v[162:165], v[80:83], v[232:235], v[162:165]
	v_mfma_f32_16x16x32_bf16 v[162:165], v[76:79], v[236:239], v[162:165]
	v_add_u32_e32 v166, s48, v115
	v_ashrrev_i32_e32 v167, 31, v166
	v_lshl_add_u64 v[166:167], v[166:167], 0, s[70:71]
	v_lshlrev_b64 v[166:167], 11, v[166:167]
	v_lshl_add_u64 v[166:167], v[178:179], 0, v[166:167]
	s_nop 8
	v_cvt_pk_bf16_f32 v168, v162, v163
	v_cvt_pk_bf16_f32 v169, v164, v165
	global_store_dwordx2 v[166:167], v[168:169], off offset:-32
	s_branch .LBB0_3088
